# fully flat grid barrier plus flag-based arrival inside each XCD (no returning atomics after the first barrier)
# baseline (speedup 1.0000x reference)
.Lxb_notfirst:
	s_add_i32 s20, s20, 1
	v_writelane_b32 v255, s20, 33
	v_sub_u32_e32 v4, 0, v3
	v_rcp_iflag_f32_e32 v5, v5
	v_add_u32_e32 v6, s8, v0
	v_mul_f32_e32 v5, 0x4f7ffffe, v5
	v_cvt_u32_f32_e32 v5, v5
	v_mul_lo_u32 v0, v4, v5
	v_mul_hi_u32 v0, v5, v0
	v_add_u32_e32 v0, v5, v0
	v_mul_hi_u32 v0, v6, v0
	v_mul_lo_u32 v4, v0, v3
	v_sub_u32_e32 v4, v6, v4
	v_add_u32_e32 v5, 1, v0
	v_cmp_ge_u32_e32 vcc, v4, v3
	s_nop 1
	v_cndmask_b32_e32 v0, v0, v5, vcc
	v_sub_u32_e32 v5, v4, v3
	v_cndmask_b32_e32 v4, v4, v5, vcc
	v_add_u32_e32 v5, 1, v0
	v_cmp_ge_u32_e32 vcc, v4, v3
	v_add_u32_e32 v4, 1, v6
	s_nop 0
	v_cndmask_b32_e32 v0, v0, v5, vcc
	v_add_u32_e32 v7, 1, v0
	v_mul_lo_u32 v5, v3, v0
	v_add_u32_e32 v3, v5, v3
	v_cmp_ne_u32_e32 vcc, v4, v3
	s_and_saveexec_b64 s[8:9], vcc
	s_xor_b64 s[8:9], exec, s[8:9]
	s_cbranch_execz .LBB0_1128
	v_readfirstlane_b32 s28, v2
	v_readfirstlane_b32 s22, v0
	s_add_i32 s22, s22, 1
	v_readlane_b32 s10, v253, 30
	v_readlane_b32 s11, v253, 31
	s_add_u32 s10, s10, 0x8000
	s_addc_u32 s11, s11, 0
	s_waitcnt lgkmcnt(0)
	s_nop 3
	buffer_inv sc1
	s_mov_b64 s[26:27], exec
	s_mov_b64 exec, 0xff
	v_mbcnt_lo_u32_b32 v6, -1, 0
	v_lshlrev_b32_e32 v6, 2, v6
